# attention output stores widened with v_permlane32_swap: 8 dwordx4 instead of 16 dwordx2 stores per 64-query tile (asm guide 7.3)
# speedup vs baseline: 1.0074x; 1.0073x over previous
; __device__ __forceinline__ unsigned cvtpk(float lo, float hi) { f32x2_t v = {lo, hi}; bf16x2_t b = __builtin_convertvector(v, bf16x2_t); return __builtin_bit_cast(unsigned, b); }
; __device__ __forceinline__ void phase4_attn(const Args& a, LAS unsigned char* lds) {
;     ...
;             int tid = tid0; asm volatile("" : "+v"(tid));
;             const int lane = tid & 63, r = lane & 31, h = lane >> 5, ql = 32 * half + r, pos = 64 * t + ql, tok = b * 2048 + pos;
;             float ss = 0.f;
; #pragma unroll
;             for (int hkv = 0; hkv < 2; ++hkv)
; #pragma unroll
;                 for (int dt = 0; dt < 2; ++dt)
; #pragma unroll
;                     for (int i = 0; i < 16; ++i) ss += comb[hkv][dt][i] * comb[hkv][dt][i];
;             ss += __shfl_xor(ss, 32);
;             if (h == 0) SSQ[w * 32 + r] = ss;
;             __syncthreads();
;             const float tot = (SSQ[(half + 0) * 32 + r] + SSQ[(half + 2) * 32 + r]) + (SSQ[(half + 4) * 32 + r] + SSQ[(half + 6) * 32 + r]);
;             const float rn = rsqrtf(tot * (1.f / 512.f) + EPS);
; #pragma unroll
;             for (int hkv = 0; hkv < 2; ++hkv)
; #pragma unroll
;                 for (int dt = 0; dt < 2; ++dt)
; #pragma unroll
;                     for (int ap = 0; ap < 4; ++ap) {
;                         u32x2 pk; pk.x = cvtpk(comb[hkv][dt][4 * ap] * rn, comb[hkv][dt][4 * ap + 1] * rn); pk.y = cvtpk(comb[hkv][dt][4 * ap + 2] * rn, comb[hkv][dt][4 * ap + 3] * rn);
;                         *(u32x2*)(o + (size_t)tok * DM + (hkv * 4 + g) * 64 + 32 * dt + 8 * ap + 4 * h) = pk;
;                     }
.LBB0_714:
	s_or_b64 exec, exec, s[0:1]
	v_or_b32_e32 v0, s79, v2
	s_waitcnt lgkmcnt(0)
	v_lshl_add_u32 v3, v0, 2, 0
	v_readlane_b32 s0, v254, 26
	v_add_u32_e32 v4, 0x22300, v3
	s_nop 0
	v_lshl_add_u32 v5, v2, 2, s0
	s_barrier
	ds_read2st64_b32 v[2:3], v5 offset0:1 offset1:2
	ds_read_b32 v6, v5 offset:768
	ds_read_b32 v4, v4
	s_mov_b32 s0, 0x800000
	v_lshlrev_b32_e32 v118, 3, v1
	s_waitcnt lgkmcnt(2)
	v_mov_b32_e32 v5, v3
	s_waitcnt lgkmcnt(1)
	v_mov_b32_e32 v3, v6
	s_waitcnt lgkmcnt(0)
	v_pk_add_f32 v[2:3], v[4:5], v[2:3]
	s_mov_b64 s[64:65], 0
	v_add_f32_e32 v2, v2, v3
	v_fmamk_f32 v2, v2, 0x3b000000, v189
	v_mul_f32_e32 v3, 0x4b800000, v2
	v_cmp_gt_f32_e32 vcc, s0, v2
	s_or_b32 s0, s24, s39
	s_lshl_b32 s24, s51, 1
	v_cndmask_b32_e32 v2, v2, v3, vcc
	v_rsq_f32_e32 v3, v2
	v_or_b32_e32 v2, s0, v0
	v_readlane_b32 s0, v254, 37
	v_readlane_b32 s1, v254, 38
	v_mul_f32_e32 v0, 0x45800000, v3
	v_cndmask_b32_e32 v0, v3, v0, vcc
	v_ashrrev_i32_e32 v3, 31, v2
	v_lshlrev_b64 v[2:3], 11, v[2:3]
	v_lshl_add_u64 v[2:3], s[0:1], 0, v[2:3]
	v_lshl_add_u64 v[2:3], v[2:3], 0, v[118:119]
	v_lshl_add_u64 v[4:5], v[2:3], 0, s[24:25]
	v_lshl_add_u64 v[28:29], v[4:5], 0, v[118:119]
	v_pk_mul_f32 v[8:9], v[148:149], v[0:1] op_sel_hi:[1,0]
	v_pk_mul_f32 v[10:11], v[150:151], v[0:1] op_sel_hi:[1,0]
	v_cvt_pk_bf16_f32 v12, v8, v9
	v_cvt_pk_bf16_f32 v13, v10, v11
	v_pk_mul_f32 v[8:9], v[146:147], v[0:1] op_sel_hi:[1,0]
	v_pk_mul_f32 v[10:11], v[144:145], v[0:1] op_sel_hi:[1,0]
	v_cvt_pk_bf16_f32 v14, v8, v9
	v_cvt_pk_bf16_f32 v15, v10, v11
	s_nop 1
	v_permlane32_swap_b32 v12, v14
	v_permlane32_swap_b32 v13, v15
	global_store_dwordx4 v[28:29], v[12:15], off
	v_pk_mul_f32 v[8:9], v[142:143], v[0:1] op_sel_hi:[1,0]
	v_pk_mul_f32 v[10:11], v[140:141], v[0:1] op_sel_hi:[1,0]
	v_cvt_pk_bf16_f32 v16, v8, v9
	v_cvt_pk_bf16_f32 v17, v10, v11
	v_pk_mul_f32 v[8:9], v[138:139], v[0:1] op_sel_hi:[1,0]
	v_pk_mul_f32 v[10:11], v[132:133], v[0:1] op_sel_hi:[1,0]
	v_cvt_pk_bf16_f32 v18, v8, v9
	v_cvt_pk_bf16_f32 v19, v10, v11
	s_nop 1
	v_permlane32_swap_b32 v16, v18
	v_permlane32_swap_b32 v17, v19
	global_store_dwordx4 v[28:29], v[16:19], off offset:32
	v_pk_mul_f32 v[8:9], v[134:135], v[0:1] op_sel_hi:[1,0]
	v_pk_mul_f32 v[10:11], v[136:137], v[0:1] op_sel_hi:[1,0]
	v_cvt_pk_bf16_f32 v20, v8, v9
	v_cvt_pk_bf16_f32 v21, v10, v11
	v_pk_mul_f32 v[8:9], v[130:131], v[0:1] op_sel_hi:[1,0]
	v_pk_mul_f32 v[10:11], v[128:129], v[0:1] op_sel_hi:[1,0]
	v_cvt_pk_bf16_f32 v22, v8, v9
	v_cvt_pk_bf16_f32 v23, v10, v11
	s_nop 1
	v_permlane32_swap_b32 v20, v22
	v_permlane32_swap_b32 v21, v23
	global_store_dwordx4 v[28:29], v[20:23], off offset:64
	v_pk_mul_f32 v[8:9], v[126:127], v[0:1] op_sel_hi:[1,0]
	v_pk_mul_f32 v[10:11], v[124:125], v[0:1] op_sel_hi:[1,0]
	v_cvt_pk_bf16_f32 v24, v8, v9
	v_cvt_pk_bf16_f32 v25, v10, v11
	v_pk_mul_f32 v[8:9], v[122:123], v[0:1] op_sel_hi:[1,0]
	v_pk_mul_f32 v[10:11], v[120:121], v[0:1] op_sel_hi:[1,0]
	v_cvt_pk_bf16_f32 v26, v8, v9
	v_cvt_pk_bf16_f32 v27, v10, v11
	s_nop 1
	v_permlane32_swap_b32 v24, v26
	v_permlane32_swap_b32 v25, v27
	global_store_dwordx4 v[28:29], v[24:27], off offset:96
	v_readlane_b32 s0, v254, 63
	v_readlane_b32 s1, v255, 0
	s_nop 1
	v_lshl_add_u64 v[2:3], s[0:1], 1, v[2:3]
	v_lshl_add_u64 v[30:31], v[2:3], 0, v[118:119]
	v_pk_mul_f32 v[8:9], v[182:183], v[0:1] op_sel_hi:[1,0]
	v_pk_mul_f32 v[10:11], v[186:187], v[0:1] op_sel_hi:[1,0]
	v_cvt_pk_bf16_f32 v12, v8, v9
	v_cvt_pk_bf16_f32 v13, v10, v11
	v_pk_mul_f32 v[8:9], v[180:181], v[0:1] op_sel_hi:[1,0]
	v_pk_mul_f32 v[10:11], v[178:179], v[0:1] op_sel_hi:[1,0]
	v_cvt_pk_bf16_f32 v14, v8, v9
	v_cvt_pk_bf16_f32 v15, v10, v11
	s_nop 1
	v_permlane32_swap_b32 v12, v14
	v_permlane32_swap_b32 v13, v15
	global_store_dwordx4 v[30:31], v[12:15], off
	v_pk_mul_f32 v[8:9], v[176:177], v[0:1] op_sel_hi:[1,0]
	v_pk_mul_f32 v[10:11], v[174:175], v[0:1] op_sel_hi:[1,0]
	v_cvt_pk_bf16_f32 v16, v8, v9
	v_cvt_pk_bf16_f32 v17, v10, v11
	v_pk_mul_f32 v[8:9], v[172:173], v[0:1] op_sel_hi:[1,0]
	v_pk_mul_f32 v[10:11], v[166:167], v[0:1] op_sel_hi:[1,0]
	v_cvt_pk_bf16_f32 v18, v8, v9
	v_cvt_pk_bf16_f32 v19, v10, v11
	s_nop 1
	v_permlane32_swap_b32 v16, v18
	v_permlane32_swap_b32 v17, v19
	global_store_dwordx4 v[30:31], v[16:19], off offset:32
	v_pk_mul_f32 v[8:9], v[168:169], v[0:1] op_sel_hi:[1,0]
	v_pk_mul_f32 v[10:11], v[170:171], v[0:1] op_sel_hi:[1,0]
	v_cvt_pk_bf16_f32 v20, v8, v9
	v_cvt_pk_bf16_f32 v21, v10, v11
	v_pk_mul_f32 v[8:9], v[164:165], v[0:1] op_sel_hi:[1,0]
	v_pk_mul_f32 v[10:11], v[162:163], v[0:1] op_sel_hi:[1,0]
	v_cvt_pk_bf16_f32 v22, v8, v9
	v_cvt_pk_bf16_f32 v23, v10, v11
	s_nop 1
	v_permlane32_swap_b32 v20, v22
	v_permlane32_swap_b32 v21, v23
	global_store_dwordx4 v[30:31], v[20:23], off offset:64
	v_pk_mul_f32 v[8:9], v[160:161], v[0:1] op_sel_hi:[1,0]
	v_pk_mul_f32 v[10:11], v[158:159], v[0:1] op_sel_hi:[1,0]
	v_cvt_pk_bf16_f32 v24, v8, v9
	v_cvt_pk_bf16_f32 v25, v10, v11
	v_pk_mul_f32 v[8:9], v[156:157], v[0:1] op_sel_hi:[1,0]
	v_pk_mul_f32 v[10:11], v[154:155], v[0:1] op_sel_hi:[1,0]
	v_cvt_pk_bf16_f32 v26, v8, v9
	v_cvt_pk_bf16_f32 v27, v10, v11
	s_nop 1
	v_permlane32_swap_b32 v24, v26
	v_permlane32_swap_b32 v25, v27
	global_store_dwordx4 v[30:31], v[24:27], off offset:96
	s_and_b64 vcc, exec, s[12:13]
	s_cbranch_vccnz .LBB0_712
